# hyena_prep fast path: 4 channels per thread via dwordx2 loads, packed f32 math, one round for all 3 arrays
# baseline (speedup 1.0000x reference)
; __device__ __forceinline__ int ltid() { int t = threadIdx.x; asm volatile("" : "+v"(t)); return t; }
; __device__ __forceinline__ void hyena_prep(const bf16_t* __restrict__ PA, const float* __restrict__ cb  , bf16_t* ZT0, bf16_t* G1T, bf16_t* G2T) {
;     const int c = ltid();
;     for (int task = blockIdx.x; task < 768; task += gridDim.x) {
;         const int arr = task >> 8, t0 = (task & 255) * 64;
;         const float w0 = cb[(arr * 3 + 0) * 512 + c], w1 = cb[(arr * 3 + 1) * 512 + c], w2 = cb[(arr * 3 + 2) * 512 + c];
;         const bf16_t* src = PA + 1536 + arr * 512 + c;
;         bf16_t* dst = (arr == 0 ? ZT0 : (arr == 1 ? G1T : G2T)) + (size_t)c * L_ + t0;
;         bf16_t raw[66];
; #pragma unroll
;         for (int k = 0; k < 66; ++k) { const int tt = t0 - 1 + k; raw[k] = (tt >= 0 && tt < L_) ? src[(size_t)tt * 3072] : (bf16_t)0; }
.LBB0_213:
	s_or_b64 exec, exec, s[4:5]
	v_readlane_b32 s0, v249, 56
	v_readlane_b32 s1, v249, 57
	v_mov_b32_e32 v0, v171
	s_andn2_b64 vcc, exec, s[0:1]
	s_cbranch_vccnz .LBB0_220
	s_cmpk_eq_i32 s16, 0x100
	s_cbranch_scc0 .Lhp_orig
	v_cmp_gt_u32_e32 vcc, 0x180, v171
	s_and_saveexec_b64 s[4:5], vcc
	s_cbranch_execz .Lhp_done
	v_readlane_b32 s0, v246, 27
	v_readlane_b32 s1, v246, 28
	v_readlane_b32 s2, v246, 25
	v_readlane_b32 s3, v246, 26
	s_nop 3
	s_lshl_b32 s20, s86, 6
	v_lshrrev_b32_e32 v243, 7, v171
	v_and_b32_e32 v184, 0x7f, v171
	v_lshlrev_b32_e32 v242, 10, v243
	v_lshl_add_u32 v242, v184, 3, v242
	v_mul_u32_u24_e32 v185, 0x1800, v243
	v_lshl_add_u32 v185, v184, 4, v185
	global_load_dwordx4 v[134:137], v185, s[2:3]
	global_load_dwordx4 v[138:141], v185, s[2:3] offset:2048
	s_add_u32 s2, s2, 0x1000
	s_addc_u32 s3, s3, 0
	global_load_dwordx4 v[142:145], v185, s[2:3]
	s_add_i32 s100, s20, -1
	s_max_i32 s100, s100, 0
	s_mul_i32 s101, s100, 0x1800
	s_mul_hi_u32 s100, s100, 0x1800
	s_add_u32 s0, s0, s101
	s_addc_u32 s1, s1, s100
	global_load_dwordx2 v[0:1], v242, s[0:1]
	s_cmp_eq_u32 s20, 0
	s_cselect_b32 s100, 0, 0x1800
	s_add_u32 s0, s0, s100
	s_addc_u32 s1, s1, 0
	global_load_dwordx2 v[2:3], v242, s[0:1]
	s_add_u32 s0, s0, 0x1800
	s_addc_u32 s1, s1, 0
	global_load_dwordx2 v[4:5], v242, s[0:1]
	s_add_u32 s0, s0, 0x1800
	s_addc_u32 s1, s1, 0
	global_load_dwordx2 v[6:7], v242, s[0:1]
	s_add_u32 s0, s0, 0x1800
	s_addc_u32 s1, s1, 0
	global_load_dwordx2 v[8:9], v242, s[0:1]
	s_add_u32 s0, s0, 0x1800
	s_addc_u32 s1, s1, 0
	global_load_dwordx2 v[10:11], v242, s[0:1]
	s_add_u32 s0, s0, 0x1800
	s_addc_u32 s1, s1, 0
	global_load_dwordx2 v[12:13], v242, s[0:1]
	s_add_u32 s0, s0, 0x1800
	s_addc_u32 s1, s1, 0
	global_load_dwordx2 v[14:15], v242, s[0:1]
	s_add_u32 s0, s0, 0x1800
	s_addc_u32 s1, s1, 0
	global_load_dwordx2 v[16:17], v242, s[0:1]
	s_add_u32 s0, s0, 0x1800
	s_addc_u32 s1, s1, 0
	global_load_dwordx2 v[18:19], v242, s[0:1]
	s_add_u32 s0, s0, 0x1800
	s_addc_u32 s1, s1, 0
	global_load_dwordx2 v[20:21], v242, s[0:1]
	s_add_u32 s0, s0, 0x1800
	s_addc_u32 s1, s1, 0
	global_load_dwordx2 v[22:23], v242, s[0:1]
	s_add_u32 s0, s0, 0x1800
	s_addc_u32 s1, s1, 0
	global_load_dwordx2 v[24:25], v242, s[0:1]
	s_add_u32 s0, s0, 0x1800
	s_addc_u32 s1, s1, 0
	global_load_dwordx2 v[26:27], v242, s[0:1]
	s_add_u32 s0, s0, 0x1800
	s_addc_u32 s1, s1, 0
	global_load_dwordx2 v[28:29], v242, s[0:1]
	s_add_u32 s0, s0, 0x1800
	s_addc_u32 s1, s1, 0
	global_load_dwordx2 v[30:31], v242, s[0:1]
	s_add_u32 s0, s0, 0x1800
	s_addc_u32 s1, s1, 0
	global_load_dwordx2 v[32:33], v242, s[0:1]
	s_add_u32 s0, s0, 0x1800
	s_addc_u32 s1, s1, 0
	global_load_dwordx2 v[34:35], v242, s[0:1]
	s_add_u32 s0, s0, 0x1800
	s_addc_u32 s1, s1, 0
	global_load_dwordx2 v[36:37], v242, s[0:1]
	s_add_u32 s0, s0, 0x1800
	s_addc_u32 s1, s1, 0
	global_load_dwordx2 v[38:39], v242, s[0:1]
	s_add_u32 s0, s0, 0x1800
	s_addc_u32 s1, s1, 0
	global_load_dwordx2 v[40:41], v242, s[0:1]
	s_add_u32 s0, s0, 0x1800
	s_addc_u32 s1, s1, 0
	global_load_dwordx2 v[42:43], v242, s[0:1]
	s_add_u32 s0, s0, 0x1800
	s_addc_u32 s1, s1, 0
	global_load_dwordx2 v[44:45], v242, s[0:1]
	s_add_u32 s0, s0, 0x1800
	s_addc_u32 s1, s1, 0
	global_load_dwordx2 v[46:47], v242, s[0:1]
	s_add_u32 s0, s0, 0x1800
	s_addc_u32 s1, s1, 0
	global_load_dwordx2 v[48:49], v242, s[0:1]
	s_add_u32 s0, s0, 0x1800
	s_addc_u32 s1, s1, 0
	global_load_dwordx2 v[50:51], v242, s[0:1]
	s_add_u32 s0, s0, 0x1800
	s_addc_u32 s1, s1, 0
	global_load_dwordx2 v[52:53], v242, s[0:1]
	s_add_u32 s0, s0, 0x1800
	s_addc_u32 s1, s1, 0
	global_load_dwordx2 v[54:55], v242, s[0:1]
	s_add_u32 s0, s0, 0x1800
	s_addc_u32 s1, s1, 0
	global_load_dwordx2 v[56:57], v242, s[0:1]
	s_add_u32 s0, s0, 0x1800
	s_addc_u32 s1, s1, 0
	global_load_dwordx2 v[58:59], v242, s[0:1]
	s_add_u32 s0, s0, 0x1800
	s_addc_u32 s1, s1, 0
	global_load_dwordx2 v[60:61], v242, s[0:1]
	s_add_u32 s0, s0, 0x1800
	s_addc_u32 s1, s1, 0
	global_load_dwordx2 v[62:63], v242, s[0:1]
	s_add_u32 s0, s0, 0x1800
	s_addc_u32 s1, s1, 0
	global_load_dwordx2 v[66:67], v242, s[0:1]
	s_add_u32 s0, s0, 0x1800
	s_addc_u32 s1, s1, 0
	global_load_dwordx2 v[68:69], v242, s[0:1]
	s_add_u32 s0, s0, 0x1800
	s_addc_u32 s1, s1, 0
	global_load_dwordx2 v[70:71], v242, s[0:1]
	s_add_u32 s0, s0, 0x1800
	s_addc_u32 s1, s1, 0
	global_load_dwordx2 v[72:73], v242, s[0:1]
	s_add_u32 s0, s0, 0x1800
	s_addc_u32 s1, s1, 0
	global_load_dwordx2 v[74:75], v242, s[0:1]
	s_add_u32 s0, s0, 0x1800
	s_addc_u32 s1, s1, 0
	global_load_dwordx2 v[76:77], v242, s[0:1]
	s_add_u32 s0, s0, 0x1800
	s_addc_u32 s1, s1, 0
	global_load_dwordx2 v[78:79], v242, s[0:1]
	s_add_u32 s0, s0, 0x1800
	s_addc_u32 s1, s1, 0
	global_load_dwordx2 v[80:81], v242, s[0:1]
	s_add_u32 s0, s0, 0x1800
	s_addc_u32 s1, s1, 0
	global_load_dwordx2 v[82:83], v242, s[0:1]
	s_add_u32 s0, s0, 0x1800
	s_addc_u32 s1, s1, 0
	global_load_dwordx2 v[84:85], v242, s[0:1]
	s_add_u32 s0, s0, 0x1800
	s_addc_u32 s1, s1, 0
	global_load_dwordx2 v[86:87], v242, s[0:1]
	s_add_u32 s0, s0, 0x1800
	s_addc_u32 s1, s1, 0
	global_load_dwordx2 v[88:89], v242, s[0:1]
	s_add_u32 s0, s0, 0x1800
	s_addc_u32 s1, s1, 0
	global_load_dwordx2 v[90:91], v242, s[0:1]
	s_add_u32 s0, s0, 0x1800
	s_addc_u32 s1, s1, 0
	global_load_dwordx2 v[92:93], v242, s[0:1]
	s_add_u32 s0, s0, 0x1800
	s_addc_u32 s1, s1, 0
	global_load_dwordx2 v[94:95], v242, s[0:1]
	s_add_u32 s0, s0, 0x1800
	s_addc_u32 s1, s1, 0
	global_load_dwordx2 v[96:97], v242, s[0:1]
	s_add_u32 s0, s0, 0x1800
	s_addc_u32 s1, s1, 0
	global_load_dwordx2 v[98:99], v242, s[0:1]
	s_add_u32 s0, s0, 0x1800
	s_addc_u32 s1, s1, 0
	global_load_dwordx2 v[100:101], v242, s[0:1]
; __device__ __forceinline__ unsigned pk2(float lo, float hi) { unsigned r; asm volatile("v_cvt_pk_bf16_f32 %0, %1, %2" : "=v"(r) : "v"(lo), "v"(hi)); return r; }
; __device__ __forceinline__ float bf2f(bf16_t v) { return __uint_as_float(((unsigned)v) << 16); }
; __device__ __forceinline__ void hyena_prep(const bf16_t* __restrict__ PA, const float* __restrict__ cb  , bf16_t* ZT0, bf16_t* G1T, bf16_t* G2T) {
;     ...
;     for (int task = blockIdx.x; task < 768; task += gridDim.x) {
;         const int arr = task >> 8, t0 = (task & 255) * 64;
;         const float w0 = cb[(arr * 3 + 0) * 512 + c], w1 = cb[(arr * 3 + 1) * 512 + c], w2 = cb[(arr * 3 + 2) * 512 + c];
;         const bf16_t* src = PA + 1536 + arr * 512 + c;
;         bf16_t* dst = (arr == 0 ? ZT0 : (arr == 1 ? G1T : G2T)) + (size_t)c * L_ + t0;
;         bf16_t raw[66];
; #pragma unroll
;         for (int k = 0; k < 66; ++k) { const int tt = t0 - 1 + k; raw[k] = (tt >= 0 && tt < L_) ? src[(size_t)tt * 3072] : (bf16_t)0; }
; #pragma unroll
;         for (int i8 = 0; i8 < 8; ++i8) {
;             float o[8];
; #pragma unroll
;             for (int k = 0; k < 8; ++k) o[k] = w0 * bf2f(raw[i8 * 8 + k]) + w1 * bf2f(raw[i8 * 8 + k + 1]) + w2 * bf2f(raw[i8 * 8 + k + 2]);
;             u32x4 w; w.x = pk2(o[0], o[1]); w.y = pk2(o[2], o[3]); w.z = pk2(o[4], o[5]); w.w = pk2(o[6], o[7]);
;             *(u32x4*)(dst + i8 * 8) = w;
;         }
	s_add_u32 s0, s0, 0x1800
	s_addc_u32 s1, s1, 0
	global_load_dwordx2 v[102:103], v242, s[0:1]
	s_add_u32 s0, s0, 0x1800
	s_addc_u32 s1, s1, 0
	global_load_dwordx2 v[104:105], v242, s[0:1]
	s_add_u32 s0, s0, 0x1800
	s_addc_u32 s1, s1, 0
	global_load_dwordx2 v[106:107], v242, s[0:1]
	s_add_u32 s0, s0, 0x1800
	s_addc_u32 s1, s1, 0
	global_load_dwordx2 v[108:109], v242, s[0:1]
	s_add_u32 s0, s0, 0x1800
	s_addc_u32 s1, s1, 0
	global_load_dwordx2 v[110:111], v242, s[0:1]
	s_add_u32 s0, s0, 0x1800
	s_addc_u32 s1, s1, 0
	global_load_dwordx2 v[112:113], v242, s[0:1]
	s_add_u32 s0, s0, 0x1800
	s_addc_u32 s1, s1, 0
	global_load_dwordx2 v[114:115], v242, s[0:1]
	s_add_u32 s0, s0, 0x1800
	s_addc_u32 s1, s1, 0
	global_load_dwordx2 v[116:117], v242, s[0:1]
	s_add_u32 s0, s0, 0x1800
	s_addc_u32 s1, s1, 0
	global_load_dwordx2 v[118:119], v242, s[0:1]
	s_add_u32 s0, s0, 0x1800
	s_addc_u32 s1, s1, 0
	global_load_dwordx2 v[120:121], v242, s[0:1]
	s_add_u32 s0, s0, 0x1800
	s_addc_u32 s1, s1, 0
	global_load_dwordx2 v[122:123], v242, s[0:1]
	s_add_u32 s0, s0, 0x1800
	s_addc_u32 s1, s1, 0
	global_load_dwordx2 v[124:125], v242, s[0:1]
	s_add_u32 s0, s0, 0x1800
	s_addc_u32 s1, s1, 0
	global_load_dwordx2 v[126:127], v242, s[0:1]
	s_add_u32 s0, s0, 0x1800
	s_addc_u32 s1, s1, 0
	global_load_dwordx2 v[128:129], v242, s[0:1]
	s_add_u32 s0, s0, 0x1800
	s_addc_u32 s1, s1, 0
	global_load_dwordx2 v[130:131], v242, s[0:1]
	s_add_u32 s0, s0, 0x1800
	s_addc_u32 s1, s1, 0
	global_load_dwordx2 v[132:133], v242, s[0:1]
	v_readlane_b32 s2, v245, 25
	v_readlane_b32 s3, v245, 26
	v_min_u32_e32 v185, 1, v243
	v_lshlrev_b32_e32 v185, 25, v185
	v_lshl_add_u32 v185, v243, 24, v185
	v_add_u32_e32 v185, 0x25b1c000, v185
	v_lshl_add_u32 v185, v184, 17, v185
	s_lshl_b32 s100, s20, 1
	v_add_u32_e32 v185, s100, v185
	v_add_u32_e32 v170, 0x8000, v185
	v_add_u32_e32 v201, 0x10000, v185
	v_add_u32_e32 v184, 0x18000, v185
	s_waitcnt vmcnt(56)
	s_cmp_eq_u32 s20, 0
	s_cbranch_scc0 .Lhp_nz0
	v_mov_b32_e32 v0, 0
	v_mov_b32_e32 v1, 0
.Lhp_nz0:
	v_lshlrev_b32_e32 v202, 16, v0
	v_and_b32_e32 v203, 0xffff0000, v0
	v_lshlrev_b32_e32 v204, 16, v1
	v_and_b32_e32 v205, 0xffff0000, v1
	v_lshlrev_b32_e32 v206, 16, v2
	v_and_b32_e32 v207, 0xffff0000, v2
	v_lshlrev_b32_e32 v208, 16, v3
	v_and_b32_e32 v209, 0xffff0000, v3
	v_lshlrev_b32_e32 v210, 16, v4
	v_and_b32_e32 v211, 0xffff0000, v4
	v_lshlrev_b32_e32 v212, 16, v5
	v_and_b32_e32 v213, 0xffff0000, v5
	v_lshlrev_b32_e32 v214, 16, v6
	v_and_b32_e32 v215, 0xffff0000, v6
	v_lshlrev_b32_e32 v216, 16, v7
	v_and_b32_e32 v217, 0xffff0000, v7
	v_lshlrev_b32_e32 v218, 16, v8
	v_and_b32_e32 v219, 0xffff0000, v8
	v_lshlrev_b32_e32 v220, 16, v9
	v_and_b32_e32 v221, 0xffff0000, v9
	v_lshlrev_b32_e32 v222, 16, v10
	v_and_b32_e32 v223, 0xffff0000, v10
	v_lshlrev_b32_e32 v224, 16, v11
	v_and_b32_e32 v225, 0xffff0000, v11
	v_lshlrev_b32_e32 v226, 16, v12
	v_and_b32_e32 v227, 0xffff0000, v12
	v_lshlrev_b32_e32 v228, 16, v13
	v_and_b32_e32 v229, 0xffff0000, v13
	v_lshlrev_b32_e32 v230, 16, v14
	v_and_b32_e32 v231, 0xffff0000, v14
	v_lshlrev_b32_e32 v232, 16, v15
	v_and_b32_e32 v233, 0xffff0000, v15
	v_lshlrev_b32_e32 v234, 16, v16
	v_and_b32_e32 v235, 0xffff0000, v16
	v_lshlrev_b32_e32 v236, 16, v17
	v_and_b32_e32 v237, 0xffff0000, v17
	v_lshlrev_b32_e32 v238, 16, v18
	v_and_b32_e32 v239, 0xffff0000, v18
	v_lshlrev_b32_e32 v240, 16, v19
	v_and_b32_e32 v241, 0xffff0000, v19
	v_pk_mul_f32 v[146:147], v[134:135], v[202:203]
	v_pk_mul_f32 v[148:149], v[136:137], v[204:205]
	v_pk_mul_f32 v[150:151], v[134:135], v[206:207]
	v_pk_mul_f32 v[152:153], v[136:137], v[208:209]
	v_pk_mul_f32 v[154:155], v[134:135], v[210:211]
	v_pk_mul_f32 v[156:157], v[136:137], v[212:213]
	v_pk_mul_f32 v[158:159], v[134:135], v[214:215]
	v_pk_mul_f32 v[160:161], v[136:137], v[216:217]
	v_pk_mul_f32 v[162:163], v[134:135], v[218:219]
	v_pk_mul_f32 v[164:165], v[136:137], v[220:221]
	v_pk_mul_f32 v[166:167], v[134:135], v[222:223]
	v_pk_mul_f32 v[168:169], v[136:137], v[224:225]
	v_pk_mul_f32 v[172:173], v[134:135], v[226:227]
	v_pk_mul_f32 v[174:175], v[136:137], v[228:229]
	v_pk_mul_f32 v[176:177], v[134:135], v[230:231]
	v_pk_mul_f32 v[178:179], v[136:137], v[232:233]
	v_pk_fma_f32 v[146:147], v[138:139], v[206:207], v[146:147]
	v_pk_fma_f32 v[148:149], v[140:141], v[208:209], v[148:149]
	v_pk_fma_f32 v[150:151], v[138:139], v[210:211], v[150:151]
	v_pk_fma_f32 v[152:153], v[140:141], v[212:213], v[152:153]
	v_pk_fma_f32 v[154:155], v[138:139], v[214:215], v[154:155]
	v_pk_fma_f32 v[156:157], v[140:141], v[216:217], v[156:157]
	v_pk_fma_f32 v[158:159], v[138:139], v[218:219], v[158:159]
	v_pk_fma_f32 v[160:161], v[140:141], v[220:221], v[160:161]
	v_pk_fma_f32 v[162:163], v[138:139], v[222:223], v[162:163]
	v_pk_fma_f32 v[164:165], v[140:141], v[224:225], v[164:165]
	v_pk_fma_f32 v[166:167], v[138:139], v[226:227], v[166:167]
	v_pk_fma_f32 v[168:169], v[140:141], v[228:229], v[168:169]
	v_pk_fma_f32 v[172:173], v[138:139], v[230:231], v[172:173]
	v_pk_fma_f32 v[174:175], v[140:141], v[232:233], v[174:175]
	v_pk_fma_f32 v[176:177], v[138:139], v[234:235], v[176:177]
	v_pk_fma_f32 v[178:179], v[140:141], v[236:237], v[178:179]
	v_pk_fma_f32 v[146:147], v[142:143], v[210:211], v[146:147]
	v_pk_fma_f32 v[148:149], v[144:145], v[212:213], v[148:149]
	v_pk_fma_f32 v[150:151], v[142:143], v[214:215], v[150:151]
	v_pk_fma_f32 v[152:153], v[144:145], v[216:217], v[152:153]
	v_pk_fma_f32 v[154:155], v[142:143], v[218:219], v[154:155]
	v_pk_fma_f32 v[156:157], v[144:145], v[220:221], v[156:157]
	v_pk_fma_f32 v[158:159], v[142:143], v[222:223], v[158:159]
	v_pk_fma_f32 v[160:161], v[144:145], v[224:225], v[160:161]
	v_pk_fma_f32 v[162:163], v[142:143], v[226:227], v[162:163]
	v_pk_fma_f32 v[164:165], v[144:145], v[228:229], v[164:165]
	v_pk_fma_f32 v[166:167], v[142:143], v[230:231], v[166:167]
	v_pk_fma_f32 v[168:169], v[144:145], v[232:233], v[168:169]
	v_pk_fma_f32 v[172:173], v[142:143], v[234:235], v[172:173]
	v_pk_fma_f32 v[174:175], v[144:145], v[236:237], v[174:175]
	v_pk_fma_f32 v[176:177], v[142:143], v[238:239], v[176:177]
	v_pk_fma_f32 v[178:179], v[144:145], v[240:241], v[178:179]
	v_cvt_pk_bf16_f32 v180, v146, v150
	v_cvt_pk_bf16_f32 v181, v154, v158
	v_cvt_pk_bf16_f32 v182, v162, v166
	v_cvt_pk_bf16_f32 v183, v172, v176
	global_store_dwordx4 v185, v[180:183], s[2:3]
	s_nop 1
	v_cvt_pk_bf16_f32 v180, v147, v151
	v_cvt_pk_bf16_f32 v181, v155, v159
	v_cvt_pk_bf16_f32 v182, v163, v167
	v_cvt_pk_bf16_f32 v183, v173, v177
	global_store_dwordx4 v170, v[180:183], s[2:3]
	s_nop 1
	v_cvt_pk_bf16_f32 v180, v148, v152
	v_cvt_pk_bf16_f32 v181, v156, v160
	v_cvt_pk_bf16_f32 v182, v164, v168
	v_cvt_pk_bf16_f32 v183, v174, v178
	global_store_dwordx4 v201, v[180:183], s[2:3]
	s_nop 1
	v_cvt_pk_bf16_f32 v180, v149, v153
	v_cvt_pk_bf16_f32 v181, v157, v161
	v_cvt_pk_bf16_f32 v182, v165, v169
	v_cvt_pk_bf16_f32 v183, v175, v179
	global_store_dwordx4 v184, v[180:183], s[2:3]
	s_nop 1
	s_waitcnt vmcnt(52)
; __device__ __forceinline__ unsigned pk2(float lo, float hi) { unsigned r; asm volatile("v_cvt_pk_bf16_f32 %0, %1, %2" : "=v"(r) : "v"(lo), "v"(hi)); return r; }
; __device__ __forceinline__ float bf2f(bf16_t v) { return __uint_as_float(((unsigned)v) << 16); }
; __device__ __forceinline__ void hyena_prep(const bf16_t* __restrict__ PA, const float* __restrict__ cb  , bf16_t* ZT0, bf16_t* G1T, bf16_t* G2T) {
;     ...
; #pragma unroll
;         for (int i8 = 0; i8 < 8; ++i8) {
;             float o[8];
; #pragma unroll
;             for (int k = 0; k < 8; ++k) o[k] = w0 * bf2f(raw[i8 * 8 + k]) + w1 * bf2f(raw[i8 * 8 + k + 1]) + w2 * bf2f(raw[i8 * 8 + k + 2]);
;             u32x4 w; w.x = pk2(o[0], o[1]); w.y = pk2(o[2], o[3]); w.z = pk2(o[4], o[5]); w.w = pk2(o[6], o[7]);
;             *(u32x4*)(dst + i8 * 8) = w;
;         }
	v_lshlrev_b32_e32 v202, 16, v16
	v_and_b32_e32 v203, 0xffff0000, v16
	v_lshlrev_b32_e32 v204, 16, v17
	v_and_b32_e32 v205, 0xffff0000, v17
	v_lshlrev_b32_e32 v206, 16, v18
	v_and_b32_e32 v207, 0xffff0000, v18
	v_lshlrev_b32_e32 v208, 16, v19
	v_and_b32_e32 v209, 0xffff0000, v19
	v_lshlrev_b32_e32 v210, 16, v20
	v_and_b32_e32 v211, 0xffff0000, v20
	v_lshlrev_b32_e32 v212, 16, v21
	v_and_b32_e32 v213, 0xffff0000, v21
	v_lshlrev_b32_e32 v214, 16, v22
	v_and_b32_e32 v215, 0xffff0000, v22
	v_lshlrev_b32_e32 v216, 16, v23
	v_and_b32_e32 v217, 0xffff0000, v23
	v_lshlrev_b32_e32 v218, 16, v24
	v_and_b32_e32 v219, 0xffff0000, v24
	v_lshlrev_b32_e32 v220, 16, v25
	v_and_b32_e32 v221, 0xffff0000, v25
	v_lshlrev_b32_e32 v222, 16, v26
	v_and_b32_e32 v223, 0xffff0000, v26
	v_lshlrev_b32_e32 v224, 16, v27
	v_and_b32_e32 v225, 0xffff0000, v27
	v_lshlrev_b32_e32 v226, 16, v28
	v_and_b32_e32 v227, 0xffff0000, v28
	v_lshlrev_b32_e32 v228, 16, v29
	v_and_b32_e32 v229, 0xffff0000, v29
	v_lshlrev_b32_e32 v230, 16, v30
	v_and_b32_e32 v231, 0xffff0000, v30
	v_lshlrev_b32_e32 v232, 16, v31
	v_and_b32_e32 v233, 0xffff0000, v31
	v_lshlrev_b32_e32 v234, 16, v32
	v_and_b32_e32 v235, 0xffff0000, v32
	v_lshlrev_b32_e32 v236, 16, v33
	v_and_b32_e32 v237, 0xffff0000, v33
	v_lshlrev_b32_e32 v238, 16, v34
	v_and_b32_e32 v239, 0xffff0000, v34
	v_lshlrev_b32_e32 v240, 16, v35
	v_and_b32_e32 v241, 0xffff0000, v35
	v_pk_mul_f32 v[146:147], v[134:135], v[202:203]
	v_pk_mul_f32 v[148:149], v[136:137], v[204:205]
	v_pk_mul_f32 v[150:151], v[134:135], v[206:207]
	v_pk_mul_f32 v[152:153], v[136:137], v[208:209]
	v_pk_mul_f32 v[154:155], v[134:135], v[210:211]
	v_pk_mul_f32 v[156:157], v[136:137], v[212:213]
	v_pk_mul_f32 v[158:159], v[134:135], v[214:215]
	v_pk_mul_f32 v[160:161], v[136:137], v[216:217]
	v_pk_mul_f32 v[162:163], v[134:135], v[218:219]
	v_pk_mul_f32 v[164:165], v[136:137], v[220:221]
	v_pk_mul_f32 v[166:167], v[134:135], v[222:223]
	v_pk_mul_f32 v[168:169], v[136:137], v[224:225]
	v_pk_mul_f32 v[172:173], v[134:135], v[226:227]
	v_pk_mul_f32 v[174:175], v[136:137], v[228:229]
	v_pk_mul_f32 v[176:177], v[134:135], v[230:231]
	v_pk_mul_f32 v[178:179], v[136:137], v[232:233]
	v_pk_fma_f32 v[146:147], v[138:139], v[206:207], v[146:147]
	v_pk_fma_f32 v[148:149], v[140:141], v[208:209], v[148:149]
	v_pk_fma_f32 v[150:151], v[138:139], v[210:211], v[150:151]
	v_pk_fma_f32 v[152:153], v[140:141], v[212:213], v[152:153]
	v_pk_fma_f32 v[154:155], v[138:139], v[214:215], v[154:155]
	v_pk_fma_f32 v[156:157], v[140:141], v[216:217], v[156:157]
	v_pk_fma_f32 v[158:159], v[138:139], v[218:219], v[158:159]
	v_pk_fma_f32 v[160:161], v[140:141], v[220:221], v[160:161]
	v_pk_fma_f32 v[162:163], v[138:139], v[222:223], v[162:163]
	v_pk_fma_f32 v[164:165], v[140:141], v[224:225], v[164:165]
	v_pk_fma_f32 v[166:167], v[138:139], v[226:227], v[166:167]
	v_pk_fma_f32 v[168:169], v[140:141], v[228:229], v[168:169]
	v_pk_fma_f32 v[172:173], v[138:139], v[230:231], v[172:173]
	v_pk_fma_f32 v[174:175], v[140:141], v[232:233], v[174:175]
	v_pk_fma_f32 v[176:177], v[138:139], v[234:235], v[176:177]
	v_pk_fma_f32 v[178:179], v[140:141], v[236:237], v[178:179]
	v_pk_fma_f32 v[146:147], v[142:143], v[210:211], v[146:147]
	v_pk_fma_f32 v[148:149], v[144:145], v[212:213], v[148:149]
	v_pk_fma_f32 v[150:151], v[142:143], v[214:215], v[150:151]
	v_pk_fma_f32 v[152:153], v[144:145], v[216:217], v[152:153]
	v_pk_fma_f32 v[154:155], v[142:143], v[218:219], v[154:155]
	v_pk_fma_f32 v[156:157], v[144:145], v[220:221], v[156:157]
	v_pk_fma_f32 v[158:159], v[142:143], v[222:223], v[158:159]
	v_pk_fma_f32 v[160:161], v[144:145], v[224:225], v[160:161]
	v_pk_fma_f32 v[162:163], v[142:143], v[226:227], v[162:163]
	v_pk_fma_f32 v[164:165], v[144:145], v[228:229], v[164:165]
	v_pk_fma_f32 v[166:167], v[142:143], v[230:231], v[166:167]
	v_pk_fma_f32 v[168:169], v[144:145], v[232:233], v[168:169]
	v_pk_fma_f32 v[172:173], v[142:143], v[234:235], v[172:173]
	v_pk_fma_f32 v[174:175], v[144:145], v[236:237], v[174:175]
	v_pk_fma_f32 v[176:177], v[142:143], v[238:239], v[176:177]
	v_pk_fma_f32 v[178:179], v[144:145], v[240:241], v[178:179]
	v_cvt_pk_bf16_f32 v180, v146, v150
	v_cvt_pk_bf16_f32 v181, v154, v158
	v_cvt_pk_bf16_f32 v182, v162, v166
	v_cvt_pk_bf16_f32 v183, v172, v176
	global_store_dwordx4 v185, v[180:183], s[2:3] offset:16
	s_nop 1
	v_cvt_pk_bf16_f32 v180, v147, v151
	v_cvt_pk_bf16_f32 v181, v155, v159
	v_cvt_pk_bf16_f32 v182, v163, v167
	v_cvt_pk_bf16_f32 v183, v173, v177
	global_store_dwordx4 v170, v[180:183], s[2:3] offset:16
	s_nop 1
	v_cvt_pk_bf16_f32 v180, v148, v152
	v_cvt_pk_bf16_f32 v181, v156, v160
	v_cvt_pk_bf16_f32 v182, v164, v168
	v_cvt_pk_bf16_f32 v183, v174, v178
	global_store_dwordx4 v201, v[180:183], s[2:3] offset:16
	s_nop 1
	v_cvt_pk_bf16_f32 v180, v149, v153
	v_cvt_pk_bf16_f32 v181, v157, v161
	v_cvt_pk_bf16_f32 v182, v165, v169
	v_cvt_pk_bf16_f32 v183, v175, v179
	global_store_dwordx4 v184, v[180:183], s[2:3] offset:16
	s_nop 1
	s_waitcnt vmcnt(48)
; __device__ __forceinline__ unsigned pk2(float lo, float hi) { unsigned r; asm volatile("v_cvt_pk_bf16_f32 %0, %1, %2" : "=v"(r) : "v"(lo), "v"(hi)); return r; }
; __device__ __forceinline__ float bf2f(bf16_t v) { return __uint_as_float(((unsigned)v) << 16); }
; __device__ __forceinline__ void hyena_prep(const bf16_t* __restrict__ PA, const float* __restrict__ cb  , bf16_t* ZT0, bf16_t* G1T, bf16_t* G2T) {
;     ...
; #pragma unroll
;         for (int i8 = 0; i8 < 8; ++i8) {
;             float o[8];
; #pragma unroll
;             for (int k = 0; k < 8; ++k) o[k] = w0 * bf2f(raw[i8 * 8 + k]) + w1 * bf2f(raw[i8 * 8 + k + 1]) + w2 * bf2f(raw[i8 * 8 + k + 2]);
;             u32x4 w; w.x = pk2(o[0], o[1]); w.y = pk2(o[2], o[3]); w.z = pk2(o[4], o[5]); w.w = pk2(o[6], o[7]);
;             *(u32x4*)(dst + i8 * 8) = w;
;         }
	v_lshlrev_b32_e32 v202, 16, v32
	v_and_b32_e32 v203, 0xffff0000, v32
	v_lshlrev_b32_e32 v204, 16, v33
	v_and_b32_e32 v205, 0xffff0000, v33
	v_lshlrev_b32_e32 v206, 16, v34
	v_and_b32_e32 v207, 0xffff0000, v34
	v_lshlrev_b32_e32 v208, 16, v35
	v_and_b32_e32 v209, 0xffff0000, v35
	v_lshlrev_b32_e32 v210, 16, v36
	v_and_b32_e32 v211, 0xffff0000, v36
	v_lshlrev_b32_e32 v212, 16, v37
	v_and_b32_e32 v213, 0xffff0000, v37
	v_lshlrev_b32_e32 v214, 16, v38
	v_and_b32_e32 v215, 0xffff0000, v38
	v_lshlrev_b32_e32 v216, 16, v39
	v_and_b32_e32 v217, 0xffff0000, v39
	v_lshlrev_b32_e32 v218, 16, v40
	v_and_b32_e32 v219, 0xffff0000, v40
	v_lshlrev_b32_e32 v220, 16, v41
	v_and_b32_e32 v221, 0xffff0000, v41
	v_lshlrev_b32_e32 v222, 16, v42
	v_and_b32_e32 v223, 0xffff0000, v42
	v_lshlrev_b32_e32 v224, 16, v43
	v_and_b32_e32 v225, 0xffff0000, v43
	v_lshlrev_b32_e32 v226, 16, v44
	v_and_b32_e32 v227, 0xffff0000, v44
	v_lshlrev_b32_e32 v228, 16, v45
	v_and_b32_e32 v229, 0xffff0000, v45
	v_lshlrev_b32_e32 v230, 16, v46
	v_and_b32_e32 v231, 0xffff0000, v46
	v_lshlrev_b32_e32 v232, 16, v47
	v_and_b32_e32 v233, 0xffff0000, v47
	v_lshlrev_b32_e32 v234, 16, v48
	v_and_b32_e32 v235, 0xffff0000, v48
	v_lshlrev_b32_e32 v236, 16, v49
	v_and_b32_e32 v237, 0xffff0000, v49
	v_lshlrev_b32_e32 v238, 16, v50
	v_and_b32_e32 v239, 0xffff0000, v50
	v_lshlrev_b32_e32 v240, 16, v51
	v_and_b32_e32 v241, 0xffff0000, v51
	v_pk_mul_f32 v[146:147], v[134:135], v[202:203]
	v_pk_mul_f32 v[148:149], v[136:137], v[204:205]
	v_pk_mul_f32 v[150:151], v[134:135], v[206:207]
	v_pk_mul_f32 v[152:153], v[136:137], v[208:209]
	v_pk_mul_f32 v[154:155], v[134:135], v[210:211]
	v_pk_mul_f32 v[156:157], v[136:137], v[212:213]
	v_pk_mul_f32 v[158:159], v[134:135], v[214:215]
	v_pk_mul_f32 v[160:161], v[136:137], v[216:217]
	v_pk_mul_f32 v[162:163], v[134:135], v[218:219]
	v_pk_mul_f32 v[164:165], v[136:137], v[220:221]
	v_pk_mul_f32 v[166:167], v[134:135], v[222:223]
	v_pk_mul_f32 v[168:169], v[136:137], v[224:225]
	v_pk_mul_f32 v[172:173], v[134:135], v[226:227]
	v_pk_mul_f32 v[174:175], v[136:137], v[228:229]
	v_pk_mul_f32 v[176:177], v[134:135], v[230:231]
	v_pk_mul_f32 v[178:179], v[136:137], v[232:233]
	v_pk_fma_f32 v[146:147], v[138:139], v[206:207], v[146:147]
	v_pk_fma_f32 v[148:149], v[140:141], v[208:209], v[148:149]
	v_pk_fma_f32 v[150:151], v[138:139], v[210:211], v[150:151]
	v_pk_fma_f32 v[152:153], v[140:141], v[212:213], v[152:153]
	v_pk_fma_f32 v[154:155], v[138:139], v[214:215], v[154:155]
	v_pk_fma_f32 v[156:157], v[140:141], v[216:217], v[156:157]
	v_pk_fma_f32 v[158:159], v[138:139], v[218:219], v[158:159]
	v_pk_fma_f32 v[160:161], v[140:141], v[220:221], v[160:161]
	v_pk_fma_f32 v[162:163], v[138:139], v[222:223], v[162:163]
	v_pk_fma_f32 v[164:165], v[140:141], v[224:225], v[164:165]
	v_pk_fma_f32 v[166:167], v[138:139], v[226:227], v[166:167]
	v_pk_fma_f32 v[168:169], v[140:141], v[228:229], v[168:169]
	v_pk_fma_f32 v[172:173], v[138:139], v[230:231], v[172:173]
	v_pk_fma_f32 v[174:175], v[140:141], v[232:233], v[174:175]
	v_pk_fma_f32 v[176:177], v[138:139], v[234:235], v[176:177]
	v_pk_fma_f32 v[178:179], v[140:141], v[236:237], v[178:179]
	v_pk_fma_f32 v[146:147], v[142:143], v[210:211], v[146:147]
	v_pk_fma_f32 v[148:149], v[144:145], v[212:213], v[148:149]
	v_pk_fma_f32 v[150:151], v[142:143], v[214:215], v[150:151]
	v_pk_fma_f32 v[152:153], v[144:145], v[216:217], v[152:153]
	v_pk_fma_f32 v[154:155], v[142:143], v[218:219], v[154:155]
	v_pk_fma_f32 v[156:157], v[144:145], v[220:221], v[156:157]
	v_pk_fma_f32 v[158:159], v[142:143], v[222:223], v[158:159]
	v_pk_fma_f32 v[160:161], v[144:145], v[224:225], v[160:161]
	v_pk_fma_f32 v[162:163], v[142:143], v[226:227], v[162:163]
	v_pk_fma_f32 v[164:165], v[144:145], v[228:229], v[164:165]
	v_pk_fma_f32 v[166:167], v[142:143], v[230:231], v[166:167]
	v_pk_fma_f32 v[168:169], v[144:145], v[232:233], v[168:169]
	v_pk_fma_f32 v[172:173], v[142:143], v[234:235], v[172:173]
	v_pk_fma_f32 v[174:175], v[144:145], v[236:237], v[174:175]
	v_pk_fma_f32 v[176:177], v[142:143], v[238:239], v[176:177]
	v_pk_fma_f32 v[178:179], v[144:145], v[240:241], v[178:179]
	v_cvt_pk_bf16_f32 v180, v146, v150
	v_cvt_pk_bf16_f32 v181, v154, v158
	v_cvt_pk_bf16_f32 v182, v162, v166
	v_cvt_pk_bf16_f32 v183, v172, v176
	global_store_dwordx4 v185, v[180:183], s[2:3] offset:32
	s_nop 1
	v_cvt_pk_bf16_f32 v180, v147, v151
	v_cvt_pk_bf16_f32 v181, v155, v159
	v_cvt_pk_bf16_f32 v182, v163, v167
	v_cvt_pk_bf16_f32 v183, v173, v177
	global_store_dwordx4 v170, v[180:183], s[2:3] offset:32
	s_nop 1
	v_cvt_pk_bf16_f32 v180, v148, v152
	v_cvt_pk_bf16_f32 v181, v156, v160
	v_cvt_pk_bf16_f32 v182, v164, v168
	v_cvt_pk_bf16_f32 v183, v174, v178
	global_store_dwordx4 v201, v[180:183], s[2:3] offset:32
	s_nop 1
	v_cvt_pk_bf16_f32 v180, v149, v153
	v_cvt_pk_bf16_f32 v181, v157, v161
	v_cvt_pk_bf16_f32 v182, v165, v169
	v_cvt_pk_bf16_f32 v183, v175, v179
	global_store_dwordx4 v184, v[180:183], s[2:3] offset:32
	s_nop 1
	s_waitcnt vmcnt(44)
; __device__ __forceinline__ unsigned pk2(float lo, float hi) { unsigned r; asm volatile("v_cvt_pk_bf16_f32 %0, %1, %2" : "=v"(r) : "v"(lo), "v"(hi)); return r; }
; __device__ __forceinline__ float bf2f(bf16_t v) { return __uint_as_float(((unsigned)v) << 16); }
; __device__ __forceinline__ void hyena_prep(const bf16_t* __restrict__ PA, const float* __restrict__ cb  , bf16_t* ZT0, bf16_t* G1T, bf16_t* G2T) {
;     ...
; #pragma unroll
;         for (int i8 = 0; i8 < 8; ++i8) {
;             float o[8];
; #pragma unroll
;             for (int k = 0; k < 8; ++k) o[k] = w0 * bf2f(raw[i8 * 8 + k]) + w1 * bf2f(raw[i8 * 8 + k + 1]) + w2 * bf2f(raw[i8 * 8 + k + 2]);
;             u32x4 w; w.x = pk2(o[0], o[1]); w.y = pk2(o[2], o[3]); w.z = pk2(o[4], o[5]); w.w = pk2(o[6], o[7]);
;             *(u32x4*)(dst + i8 * 8) = w;
;         }
	v_lshlrev_b32_e32 v202, 16, v48
	v_and_b32_e32 v203, 0xffff0000, v48
	v_lshlrev_b32_e32 v204, 16, v49
	v_and_b32_e32 v205, 0xffff0000, v49
	v_lshlrev_b32_e32 v206, 16, v50
	v_and_b32_e32 v207, 0xffff0000, v50
	v_lshlrev_b32_e32 v208, 16, v51
	v_and_b32_e32 v209, 0xffff0000, v51
	v_lshlrev_b32_e32 v210, 16, v52
	v_and_b32_e32 v211, 0xffff0000, v52
	v_lshlrev_b32_e32 v212, 16, v53
	v_and_b32_e32 v213, 0xffff0000, v53
	v_lshlrev_b32_e32 v214, 16, v54
	v_and_b32_e32 v215, 0xffff0000, v54
	v_lshlrev_b32_e32 v216, 16, v55
	v_and_b32_e32 v217, 0xffff0000, v55
	v_lshlrev_b32_e32 v218, 16, v56
	v_and_b32_e32 v219, 0xffff0000, v56
	v_lshlrev_b32_e32 v220, 16, v57
	v_and_b32_e32 v221, 0xffff0000, v57
	v_lshlrev_b32_e32 v222, 16, v58
	v_and_b32_e32 v223, 0xffff0000, v58
	v_lshlrev_b32_e32 v224, 16, v59
	v_and_b32_e32 v225, 0xffff0000, v59
	v_lshlrev_b32_e32 v226, 16, v60
	v_and_b32_e32 v227, 0xffff0000, v60
	v_lshlrev_b32_e32 v228, 16, v61
	v_and_b32_e32 v229, 0xffff0000, v61
	v_lshlrev_b32_e32 v230, 16, v62
	v_and_b32_e32 v231, 0xffff0000, v62
	v_lshlrev_b32_e32 v232, 16, v63
	v_and_b32_e32 v233, 0xffff0000, v63
	v_lshlrev_b32_e32 v234, 16, v66
	v_and_b32_e32 v235, 0xffff0000, v66
	v_lshlrev_b32_e32 v236, 16, v67
	v_and_b32_e32 v237, 0xffff0000, v67
	v_lshlrev_b32_e32 v238, 16, v68
	v_and_b32_e32 v239, 0xffff0000, v68
	v_lshlrev_b32_e32 v240, 16, v69
	v_and_b32_e32 v241, 0xffff0000, v69
	v_pk_mul_f32 v[146:147], v[134:135], v[202:203]
	v_pk_mul_f32 v[148:149], v[136:137], v[204:205]
	v_pk_mul_f32 v[150:151], v[134:135], v[206:207]
	v_pk_mul_f32 v[152:153], v[136:137], v[208:209]
	v_pk_mul_f32 v[154:155], v[134:135], v[210:211]
	v_pk_mul_f32 v[156:157], v[136:137], v[212:213]
	v_pk_mul_f32 v[158:159], v[134:135], v[214:215]
	v_pk_mul_f32 v[160:161], v[136:137], v[216:217]
	v_pk_mul_f32 v[162:163], v[134:135], v[218:219]
	v_pk_mul_f32 v[164:165], v[136:137], v[220:221]
	v_pk_mul_f32 v[166:167], v[134:135], v[222:223]
	v_pk_mul_f32 v[168:169], v[136:137], v[224:225]
	v_pk_mul_f32 v[172:173], v[134:135], v[226:227]
	v_pk_mul_f32 v[174:175], v[136:137], v[228:229]
	v_pk_mul_f32 v[176:177], v[134:135], v[230:231]
	v_pk_mul_f32 v[178:179], v[136:137], v[232:233]
	v_pk_fma_f32 v[146:147], v[138:139], v[206:207], v[146:147]
	v_pk_fma_f32 v[148:149], v[140:141], v[208:209], v[148:149]
	v_pk_fma_f32 v[150:151], v[138:139], v[210:211], v[150:151]
	v_pk_fma_f32 v[152:153], v[140:141], v[212:213], v[152:153]
	v_pk_fma_f32 v[154:155], v[138:139], v[214:215], v[154:155]
	v_pk_fma_f32 v[156:157], v[140:141], v[216:217], v[156:157]
	v_pk_fma_f32 v[158:159], v[138:139], v[218:219], v[158:159]
	v_pk_fma_f32 v[160:161], v[140:141], v[220:221], v[160:161]
	v_pk_fma_f32 v[162:163], v[138:139], v[222:223], v[162:163]
	v_pk_fma_f32 v[164:165], v[140:141], v[224:225], v[164:165]
	v_pk_fma_f32 v[166:167], v[138:139], v[226:227], v[166:167]
	v_pk_fma_f32 v[168:169], v[140:141], v[228:229], v[168:169]
	v_pk_fma_f32 v[172:173], v[138:139], v[230:231], v[172:173]
	v_pk_fma_f32 v[174:175], v[140:141], v[232:233], v[174:175]
	v_pk_fma_f32 v[176:177], v[138:139], v[234:235], v[176:177]
	v_pk_fma_f32 v[178:179], v[140:141], v[236:237], v[178:179]
	v_pk_fma_f32 v[146:147], v[142:143], v[210:211], v[146:147]
	v_pk_fma_f32 v[148:149], v[144:145], v[212:213], v[148:149]
	v_pk_fma_f32 v[150:151], v[142:143], v[214:215], v[150:151]
	v_pk_fma_f32 v[152:153], v[144:145], v[216:217], v[152:153]
	v_pk_fma_f32 v[154:155], v[142:143], v[218:219], v[154:155]
	v_pk_fma_f32 v[156:157], v[144:145], v[220:221], v[156:157]
	v_pk_fma_f32 v[158:159], v[142:143], v[222:223], v[158:159]
	v_pk_fma_f32 v[160:161], v[144:145], v[224:225], v[160:161]
	v_pk_fma_f32 v[162:163], v[142:143], v[226:227], v[162:163]
	v_pk_fma_f32 v[164:165], v[144:145], v[228:229], v[164:165]
	v_pk_fma_f32 v[166:167], v[142:143], v[230:231], v[166:167]
	v_pk_fma_f32 v[168:169], v[144:145], v[232:233], v[168:169]
	v_pk_fma_f32 v[172:173], v[142:143], v[234:235], v[172:173]
	v_pk_fma_f32 v[174:175], v[144:145], v[236:237], v[174:175]
	v_pk_fma_f32 v[176:177], v[142:143], v[238:239], v[176:177]
	v_pk_fma_f32 v[178:179], v[144:145], v[240:241], v[178:179]
	v_cvt_pk_bf16_f32 v180, v146, v150
	v_cvt_pk_bf16_f32 v181, v154, v158
	v_cvt_pk_bf16_f32 v182, v162, v166
	v_cvt_pk_bf16_f32 v183, v172, v176
	global_store_dwordx4 v185, v[180:183], s[2:3] offset:48
	s_nop 1
	v_cvt_pk_bf16_f32 v180, v147, v151
	v_cvt_pk_bf16_f32 v181, v155, v159
	v_cvt_pk_bf16_f32 v182, v163, v167
	v_cvt_pk_bf16_f32 v183, v173, v177
	global_store_dwordx4 v170, v[180:183], s[2:3] offset:48
	s_nop 1
	v_cvt_pk_bf16_f32 v180, v148, v152
	v_cvt_pk_bf16_f32 v181, v156, v160
	v_cvt_pk_bf16_f32 v182, v164, v168
	v_cvt_pk_bf16_f32 v183, v174, v178
	global_store_dwordx4 v201, v[180:183], s[2:3] offset:48
	s_nop 1
	v_cvt_pk_bf16_f32 v180, v149, v153
	v_cvt_pk_bf16_f32 v181, v157, v161
	v_cvt_pk_bf16_f32 v182, v165, v169
	v_cvt_pk_bf16_f32 v183, v175, v179
	global_store_dwordx4 v184, v[180:183], s[2:3] offset:48
	s_nop 1
	s_waitcnt vmcnt(40)
; __device__ __forceinline__ unsigned pk2(float lo, float hi) { unsigned r; asm volatile("v_cvt_pk_bf16_f32 %0, %1, %2" : "=v"(r) : "v"(lo), "v"(hi)); return r; }
; __device__ __forceinline__ float bf2f(bf16_t v) { return __uint_as_float(((unsigned)v) << 16); }
; __device__ __forceinline__ void hyena_prep(const bf16_t* __restrict__ PA, const float* __restrict__ cb  , bf16_t* ZT0, bf16_t* G1T, bf16_t* G2T) {
;     ...
; #pragma unroll
;         for (int i8 = 0; i8 < 8; ++i8) {
;             float o[8];
; #pragma unroll
;             for (int k = 0; k < 8; ++k) o[k] = w0 * bf2f(raw[i8 * 8 + k]) + w1 * bf2f(raw[i8 * 8 + k + 1]) + w2 * bf2f(raw[i8 * 8 + k + 2]);
;             u32x4 w; w.x = pk2(o[0], o[1]); w.y = pk2(o[2], o[3]); w.z = pk2(o[4], o[5]); w.w = pk2(o[6], o[7]);
;             *(u32x4*)(dst + i8 * 8) = w;
;         }
	v_lshlrev_b32_e32 v202, 16, v66
	v_and_b32_e32 v203, 0xffff0000, v66
	v_lshlrev_b32_e32 v204, 16, v67
	v_and_b32_e32 v205, 0xffff0000, v67
	v_lshlrev_b32_e32 v206, 16, v68
	v_and_b32_e32 v207, 0xffff0000, v68
	v_lshlrev_b32_e32 v208, 16, v69
	v_and_b32_e32 v209, 0xffff0000, v69
	v_lshlrev_b32_e32 v210, 16, v70
	v_and_b32_e32 v211, 0xffff0000, v70
	v_lshlrev_b32_e32 v212, 16, v71
	v_and_b32_e32 v213, 0xffff0000, v71
	v_lshlrev_b32_e32 v214, 16, v72
	v_and_b32_e32 v215, 0xffff0000, v72
	v_lshlrev_b32_e32 v216, 16, v73
	v_and_b32_e32 v217, 0xffff0000, v73
	v_lshlrev_b32_e32 v218, 16, v74
	v_and_b32_e32 v219, 0xffff0000, v74
	v_lshlrev_b32_e32 v220, 16, v75
	v_and_b32_e32 v221, 0xffff0000, v75
	v_lshlrev_b32_e32 v222, 16, v76
	v_and_b32_e32 v223, 0xffff0000, v76
	v_lshlrev_b32_e32 v224, 16, v77
	v_and_b32_e32 v225, 0xffff0000, v77
	v_lshlrev_b32_e32 v226, 16, v78
	v_and_b32_e32 v227, 0xffff0000, v78
	v_lshlrev_b32_e32 v228, 16, v79
	v_and_b32_e32 v229, 0xffff0000, v79
	v_lshlrev_b32_e32 v230, 16, v80
	v_and_b32_e32 v231, 0xffff0000, v80
	v_lshlrev_b32_e32 v232, 16, v81
	v_and_b32_e32 v233, 0xffff0000, v81
	v_lshlrev_b32_e32 v234, 16, v82
	v_and_b32_e32 v235, 0xffff0000, v82
	v_lshlrev_b32_e32 v236, 16, v83
	v_and_b32_e32 v237, 0xffff0000, v83
	v_lshlrev_b32_e32 v238, 16, v84
	v_and_b32_e32 v239, 0xffff0000, v84
	v_lshlrev_b32_e32 v240, 16, v85
	v_and_b32_e32 v241, 0xffff0000, v85
	v_pk_mul_f32 v[146:147], v[134:135], v[202:203]
	v_pk_mul_f32 v[148:149], v[136:137], v[204:205]
	v_pk_mul_f32 v[150:151], v[134:135], v[206:207]
	v_pk_mul_f32 v[152:153], v[136:137], v[208:209]
	v_pk_mul_f32 v[154:155], v[134:135], v[210:211]
	v_pk_mul_f32 v[156:157], v[136:137], v[212:213]
	v_pk_mul_f32 v[158:159], v[134:135], v[214:215]
	v_pk_mul_f32 v[160:161], v[136:137], v[216:217]
	v_pk_mul_f32 v[162:163], v[134:135], v[218:219]
	v_pk_mul_f32 v[164:165], v[136:137], v[220:221]
	v_pk_mul_f32 v[166:167], v[134:135], v[222:223]
	v_pk_mul_f32 v[168:169], v[136:137], v[224:225]
	v_pk_mul_f32 v[172:173], v[134:135], v[226:227]
	v_pk_mul_f32 v[174:175], v[136:137], v[228:229]
	v_pk_mul_f32 v[176:177], v[134:135], v[230:231]
	v_pk_mul_f32 v[178:179], v[136:137], v[232:233]
	v_pk_fma_f32 v[146:147], v[138:139], v[206:207], v[146:147]
	v_pk_fma_f32 v[148:149], v[140:141], v[208:209], v[148:149]
	v_pk_fma_f32 v[150:151], v[138:139], v[210:211], v[150:151]
	v_pk_fma_f32 v[152:153], v[140:141], v[212:213], v[152:153]
	v_pk_fma_f32 v[154:155], v[138:139], v[214:215], v[154:155]
	v_pk_fma_f32 v[156:157], v[140:141], v[216:217], v[156:157]
	v_pk_fma_f32 v[158:159], v[138:139], v[218:219], v[158:159]
	v_pk_fma_f32 v[160:161], v[140:141], v[220:221], v[160:161]
	v_pk_fma_f32 v[162:163], v[138:139], v[222:223], v[162:163]
	v_pk_fma_f32 v[164:165], v[140:141], v[224:225], v[164:165]
	v_pk_fma_f32 v[166:167], v[138:139], v[226:227], v[166:167]
	v_pk_fma_f32 v[168:169], v[140:141], v[228:229], v[168:169]
	v_pk_fma_f32 v[172:173], v[138:139], v[230:231], v[172:173]
	v_pk_fma_f32 v[174:175], v[140:141], v[232:233], v[174:175]
	v_pk_fma_f32 v[176:177], v[138:139], v[234:235], v[176:177]
	v_pk_fma_f32 v[178:179], v[140:141], v[236:237], v[178:179]
	v_pk_fma_f32 v[146:147], v[142:143], v[210:211], v[146:147]
	v_pk_fma_f32 v[148:149], v[144:145], v[212:213], v[148:149]
	v_pk_fma_f32 v[150:151], v[142:143], v[214:215], v[150:151]
	v_pk_fma_f32 v[152:153], v[144:145], v[216:217], v[152:153]
	v_pk_fma_f32 v[154:155], v[142:143], v[218:219], v[154:155]
	v_pk_fma_f32 v[156:157], v[144:145], v[220:221], v[156:157]
	v_pk_fma_f32 v[158:159], v[142:143], v[222:223], v[158:159]
	v_pk_fma_f32 v[160:161], v[144:145], v[224:225], v[160:161]
	v_pk_fma_f32 v[162:163], v[142:143], v[226:227], v[162:163]
	v_pk_fma_f32 v[164:165], v[144:145], v[228:229], v[164:165]
	v_pk_fma_f32 v[166:167], v[142:143], v[230:231], v[166:167]
	v_pk_fma_f32 v[168:169], v[144:145], v[232:233], v[168:169]
	v_pk_fma_f32 v[172:173], v[142:143], v[234:235], v[172:173]
	v_pk_fma_f32 v[174:175], v[144:145], v[236:237], v[174:175]
	v_pk_fma_f32 v[176:177], v[142:143], v[238:239], v[176:177]
	v_pk_fma_f32 v[178:179], v[144:145], v[240:241], v[178:179]
	v_cvt_pk_bf16_f32 v180, v146, v150
	v_cvt_pk_bf16_f32 v181, v154, v158
	v_cvt_pk_bf16_f32 v182, v162, v166
	v_cvt_pk_bf16_f32 v183, v172, v176
	global_store_dwordx4 v185, v[180:183], s[2:3] offset:64
	s_nop 1
	v_cvt_pk_bf16_f32 v180, v147, v151
	v_cvt_pk_bf16_f32 v181, v155, v159
	v_cvt_pk_bf16_f32 v182, v163, v167
	v_cvt_pk_bf16_f32 v183, v173, v177
	global_store_dwordx4 v170, v[180:183], s[2:3] offset:64
	s_nop 1
	v_cvt_pk_bf16_f32 v180, v148, v152
	v_cvt_pk_bf16_f32 v181, v156, v160
	v_cvt_pk_bf16_f32 v182, v164, v168
	v_cvt_pk_bf16_f32 v183, v174, v178
	global_store_dwordx4 v201, v[180:183], s[2:3] offset:64
	s_nop 1
	v_cvt_pk_bf16_f32 v180, v149, v153
	v_cvt_pk_bf16_f32 v181, v157, v161
	v_cvt_pk_bf16_f32 v182, v165, v169
	v_cvt_pk_bf16_f32 v183, v175, v179
	global_store_dwordx4 v184, v[180:183], s[2:3] offset:64
	s_nop 1
	s_waitcnt vmcnt(36)
; __device__ __forceinline__ unsigned pk2(float lo, float hi) { unsigned r; asm volatile("v_cvt_pk_bf16_f32 %0, %1, %2" : "=v"(r) : "v"(lo), "v"(hi)); return r; }
; __device__ __forceinline__ float bf2f(bf16_t v) { return __uint_as_float(((unsigned)v) << 16); }
; __device__ __forceinline__ void hyena_prep(const bf16_t* __restrict__ PA, const float* __restrict__ cb  , bf16_t* ZT0, bf16_t* G1T, bf16_t* G2T) {
;     ...
; #pragma unroll
;         for (int i8 = 0; i8 < 8; ++i8) {
;             float o[8];
; #pragma unroll
;             for (int k = 0; k < 8; ++k) o[k] = w0 * bf2f(raw[i8 * 8 + k]) + w1 * bf2f(raw[i8 * 8 + k + 1]) + w2 * bf2f(raw[i8 * 8 + k + 2]);
;             u32x4 w; w.x = pk2(o[0], o[1]); w.y = pk2(o[2], o[3]); w.z = pk2(o[4], o[5]); w.w = pk2(o[6], o[7]);
;             *(u32x4*)(dst + i8 * 8) = w;
;         }
	v_lshlrev_b32_e32 v202, 16, v82
	v_and_b32_e32 v203, 0xffff0000, v82
	v_lshlrev_b32_e32 v204, 16, v83
	v_and_b32_e32 v205, 0xffff0000, v83
	v_lshlrev_b32_e32 v206, 16, v84
	v_and_b32_e32 v207, 0xffff0000, v84
	v_lshlrev_b32_e32 v208, 16, v85
	v_and_b32_e32 v209, 0xffff0000, v85
	v_lshlrev_b32_e32 v210, 16, v86
	v_and_b32_e32 v211, 0xffff0000, v86
	v_lshlrev_b32_e32 v212, 16, v87
	v_and_b32_e32 v213, 0xffff0000, v87
	v_lshlrev_b32_e32 v214, 16, v88
	v_and_b32_e32 v215, 0xffff0000, v88
	v_lshlrev_b32_e32 v216, 16, v89
	v_and_b32_e32 v217, 0xffff0000, v89
	v_lshlrev_b32_e32 v218, 16, v90
	v_and_b32_e32 v219, 0xffff0000, v90
	v_lshlrev_b32_e32 v220, 16, v91
	v_and_b32_e32 v221, 0xffff0000, v91
	v_lshlrev_b32_e32 v222, 16, v92
	v_and_b32_e32 v223, 0xffff0000, v92
	v_lshlrev_b32_e32 v224, 16, v93
	v_and_b32_e32 v225, 0xffff0000, v93
	v_lshlrev_b32_e32 v226, 16, v94
	v_and_b32_e32 v227, 0xffff0000, v94
	v_lshlrev_b32_e32 v228, 16, v95
	v_and_b32_e32 v229, 0xffff0000, v95
	v_lshlrev_b32_e32 v230, 16, v96
	v_and_b32_e32 v231, 0xffff0000, v96
	v_lshlrev_b32_e32 v232, 16, v97
	v_and_b32_e32 v233, 0xffff0000, v97
	v_lshlrev_b32_e32 v234, 16, v98
	v_and_b32_e32 v235, 0xffff0000, v98
	v_lshlrev_b32_e32 v236, 16, v99
	v_and_b32_e32 v237, 0xffff0000, v99
	v_lshlrev_b32_e32 v238, 16, v100
	v_and_b32_e32 v239, 0xffff0000, v100
	v_lshlrev_b32_e32 v240, 16, v101
	v_and_b32_e32 v241, 0xffff0000, v101
	v_pk_mul_f32 v[146:147], v[134:135], v[202:203]
	v_pk_mul_f32 v[148:149], v[136:137], v[204:205]
	v_pk_mul_f32 v[150:151], v[134:135], v[206:207]
	v_pk_mul_f32 v[152:153], v[136:137], v[208:209]
	v_pk_mul_f32 v[154:155], v[134:135], v[210:211]
	v_pk_mul_f32 v[156:157], v[136:137], v[212:213]
	v_pk_mul_f32 v[158:159], v[134:135], v[214:215]
	v_pk_mul_f32 v[160:161], v[136:137], v[216:217]
	v_pk_mul_f32 v[162:163], v[134:135], v[218:219]
	v_pk_mul_f32 v[164:165], v[136:137], v[220:221]
	v_pk_mul_f32 v[166:167], v[134:135], v[222:223]
	v_pk_mul_f32 v[168:169], v[136:137], v[224:225]
	v_pk_mul_f32 v[172:173], v[134:135], v[226:227]
	v_pk_mul_f32 v[174:175], v[136:137], v[228:229]
	v_pk_mul_f32 v[176:177], v[134:135], v[230:231]
	v_pk_mul_f32 v[178:179], v[136:137], v[232:233]
	v_pk_fma_f32 v[146:147], v[138:139], v[206:207], v[146:147]
	v_pk_fma_f32 v[148:149], v[140:141], v[208:209], v[148:149]
	v_pk_fma_f32 v[150:151], v[138:139], v[210:211], v[150:151]
	v_pk_fma_f32 v[152:153], v[140:141], v[212:213], v[152:153]
	v_pk_fma_f32 v[154:155], v[138:139], v[214:215], v[154:155]
	v_pk_fma_f32 v[156:157], v[140:141], v[216:217], v[156:157]
	v_pk_fma_f32 v[158:159], v[138:139], v[218:219], v[158:159]
	v_pk_fma_f32 v[160:161], v[140:141], v[220:221], v[160:161]
	v_pk_fma_f32 v[162:163], v[138:139], v[222:223], v[162:163]
	v_pk_fma_f32 v[164:165], v[140:141], v[224:225], v[164:165]
	v_pk_fma_f32 v[166:167], v[138:139], v[226:227], v[166:167]
	v_pk_fma_f32 v[168:169], v[140:141], v[228:229], v[168:169]
	v_pk_fma_f32 v[172:173], v[138:139], v[230:231], v[172:173]
	v_pk_fma_f32 v[174:175], v[140:141], v[232:233], v[174:175]
	v_pk_fma_f32 v[176:177], v[138:139], v[234:235], v[176:177]
	v_pk_fma_f32 v[178:179], v[140:141], v[236:237], v[178:179]
	v_pk_fma_f32 v[146:147], v[142:143], v[210:211], v[146:147]
	v_pk_fma_f32 v[148:149], v[144:145], v[212:213], v[148:149]
	v_pk_fma_f32 v[150:151], v[142:143], v[214:215], v[150:151]
	v_pk_fma_f32 v[152:153], v[144:145], v[216:217], v[152:153]
	v_pk_fma_f32 v[154:155], v[142:143], v[218:219], v[154:155]
	v_pk_fma_f32 v[156:157], v[144:145], v[220:221], v[156:157]
	v_pk_fma_f32 v[158:159], v[142:143], v[222:223], v[158:159]
	v_pk_fma_f32 v[160:161], v[144:145], v[224:225], v[160:161]
	v_pk_fma_f32 v[162:163], v[142:143], v[226:227], v[162:163]
	v_pk_fma_f32 v[164:165], v[144:145], v[228:229], v[164:165]
	v_pk_fma_f32 v[166:167], v[142:143], v[230:231], v[166:167]
	v_pk_fma_f32 v[168:169], v[144:145], v[232:233], v[168:169]
	v_pk_fma_f32 v[172:173], v[142:143], v[234:235], v[172:173]
	v_pk_fma_f32 v[174:175], v[144:145], v[236:237], v[174:175]
	v_pk_fma_f32 v[176:177], v[142:143], v[238:239], v[176:177]
	v_pk_fma_f32 v[178:179], v[144:145], v[240:241], v[178:179]
	v_cvt_pk_bf16_f32 v180, v146, v150
	v_cvt_pk_bf16_f32 v181, v154, v158
	v_cvt_pk_bf16_f32 v182, v162, v166
	v_cvt_pk_bf16_f32 v183, v172, v176
	global_store_dwordx4 v185, v[180:183], s[2:3] offset:80
	s_nop 1
	v_cvt_pk_bf16_f32 v180, v147, v151
	v_cvt_pk_bf16_f32 v181, v155, v159
	v_cvt_pk_bf16_f32 v182, v163, v167
	v_cvt_pk_bf16_f32 v183, v173, v177
	global_store_dwordx4 v170, v[180:183], s[2:3] offset:80
	s_nop 1
	v_cvt_pk_bf16_f32 v180, v148, v152
	v_cvt_pk_bf16_f32 v181, v156, v160
	v_cvt_pk_bf16_f32 v182, v164, v168
	v_cvt_pk_bf16_f32 v183, v174, v178
	global_store_dwordx4 v201, v[180:183], s[2:3] offset:80
	s_nop 1
	v_cvt_pk_bf16_f32 v180, v149, v153
	v_cvt_pk_bf16_f32 v181, v157, v161
	v_cvt_pk_bf16_f32 v182, v165, v169
	v_cvt_pk_bf16_f32 v183, v175, v179
	global_store_dwordx4 v184, v[180:183], s[2:3] offset:80
	s_nop 1
	s_waitcnt vmcnt(32)
; __device__ __forceinline__ unsigned pk2(float lo, float hi) { unsigned r; asm volatile("v_cvt_pk_bf16_f32 %0, %1, %2" : "=v"(r) : "v"(lo), "v"(hi)); return r; }
; __device__ __forceinline__ float bf2f(bf16_t v) { return __uint_as_float(((unsigned)v) << 16); }
; __device__ __forceinline__ void hyena_prep(const bf16_t* __restrict__ PA, const float* __restrict__ cb  , bf16_t* ZT0, bf16_t* G1T, bf16_t* G2T) {
;     ...
;         for (int k = 0; k < 66; ++k) { const int tt = t0 - 1 + k; raw[k] = (tt >= 0 && tt < L_) ? src[(size_t)tt * 3072] : (bf16_t)0; }
; #pragma unroll
;         for (int i8 = 0; i8 < 8; ++i8) {
;             float o[8];
; #pragma unroll
;             for (int k = 0; k < 8; ++k) o[k] = w0 * bf2f(raw[i8 * 8 + k]) + w1 * bf2f(raw[i8 * 8 + k + 1]) + w2 * bf2f(raw[i8 * 8 + k + 2]);
;             u32x4 w; w.x = pk2(o[0], o[1]); w.y = pk2(o[2], o[3]); w.z = pk2(o[4], o[5]); w.w = pk2(o[6], o[7]);
;             *(u32x4*)(dst + i8 * 8) = w;
;         }
	v_lshlrev_b32_e32 v202, 16, v98
	v_and_b32_e32 v203, 0xffff0000, v98
	v_lshlrev_b32_e32 v204, 16, v99
	v_and_b32_e32 v205, 0xffff0000, v99
	v_lshlrev_b32_e32 v206, 16, v100
	v_and_b32_e32 v207, 0xffff0000, v100
	v_lshlrev_b32_e32 v208, 16, v101
	v_and_b32_e32 v209, 0xffff0000, v101
	v_lshlrev_b32_e32 v210, 16, v102
	v_and_b32_e32 v211, 0xffff0000, v102
	v_lshlrev_b32_e32 v212, 16, v103
	v_and_b32_e32 v213, 0xffff0000, v103
	v_lshlrev_b32_e32 v214, 16, v104
	v_and_b32_e32 v215, 0xffff0000, v104
	v_lshlrev_b32_e32 v216, 16, v105
	v_and_b32_e32 v217, 0xffff0000, v105
	v_lshlrev_b32_e32 v218, 16, v106
	v_and_b32_e32 v219, 0xffff0000, v106
	v_lshlrev_b32_e32 v220, 16, v107
	v_and_b32_e32 v221, 0xffff0000, v107
	v_lshlrev_b32_e32 v222, 16, v108
	v_and_b32_e32 v223, 0xffff0000, v108
	v_lshlrev_b32_e32 v224, 16, v109
	v_and_b32_e32 v225, 0xffff0000, v109
	v_lshlrev_b32_e32 v226, 16, v110
	v_and_b32_e32 v227, 0xffff0000, v110
	v_lshlrev_b32_e32 v228, 16, v111
	v_and_b32_e32 v229, 0xffff0000, v111
	v_lshlrev_b32_e32 v230, 16, v112
	v_and_b32_e32 v231, 0xffff0000, v112
	v_lshlrev_b32_e32 v232, 16, v113
	v_and_b32_e32 v233, 0xffff0000, v113
	v_lshlrev_b32_e32 v234, 16, v114
	v_and_b32_e32 v235, 0xffff0000, v114
	v_lshlrev_b32_e32 v236, 16, v115
	v_and_b32_e32 v237, 0xffff0000, v115
	v_lshlrev_b32_e32 v238, 16, v116
	v_and_b32_e32 v239, 0xffff0000, v116
	v_lshlrev_b32_e32 v240, 16, v117
	v_and_b32_e32 v241, 0xffff0000, v117
	v_pk_mul_f32 v[146:147], v[134:135], v[202:203]
	v_pk_mul_f32 v[148:149], v[136:137], v[204:205]
	v_pk_mul_f32 v[150:151], v[134:135], v[206:207]
	v_pk_mul_f32 v[152:153], v[136:137], v[208:209]
	v_pk_mul_f32 v[154:155], v[134:135], v[210:211]
	v_pk_mul_f32 v[156:157], v[136:137], v[212:213]
	v_pk_mul_f32 v[158:159], v[134:135], v[214:215]
	v_pk_mul_f32 v[160:161], v[136:137], v[216:217]
	v_pk_mul_f32 v[162:163], v[134:135], v[218:219]
	v_pk_mul_f32 v[164:165], v[136:137], v[220:221]
	v_pk_mul_f32 v[166:167], v[134:135], v[222:223]
	v_pk_mul_f32 v[168:169], v[136:137], v[224:225]
	v_pk_mul_f32 v[172:173], v[134:135], v[226:227]
	v_pk_mul_f32 v[174:175], v[136:137], v[228:229]
	v_pk_mul_f32 v[176:177], v[134:135], v[230:231]
	v_pk_mul_f32 v[178:179], v[136:137], v[232:233]
	v_pk_fma_f32 v[146:147], v[138:139], v[206:207], v[146:147]
	v_pk_fma_f32 v[148:149], v[140:141], v[208:209], v[148:149]
	v_pk_fma_f32 v[150:151], v[138:139], v[210:211], v[150:151]
	v_pk_fma_f32 v[152:153], v[140:141], v[212:213], v[152:153]
	v_pk_fma_f32 v[154:155], v[138:139], v[214:215], v[154:155]
	v_pk_fma_f32 v[156:157], v[140:141], v[216:217], v[156:157]
	v_pk_fma_f32 v[158:159], v[138:139], v[218:219], v[158:159]
	v_pk_fma_f32 v[160:161], v[140:141], v[220:221], v[160:161]
	v_pk_fma_f32 v[162:163], v[138:139], v[222:223], v[162:163]
	v_pk_fma_f32 v[164:165], v[140:141], v[224:225], v[164:165]
	v_pk_fma_f32 v[166:167], v[138:139], v[226:227], v[166:167]
	v_pk_fma_f32 v[168:169], v[140:141], v[228:229], v[168:169]
	v_pk_fma_f32 v[172:173], v[138:139], v[230:231], v[172:173]
	v_pk_fma_f32 v[174:175], v[140:141], v[232:233], v[174:175]
	v_pk_fma_f32 v[176:177], v[138:139], v[234:235], v[176:177]
	v_pk_fma_f32 v[178:179], v[140:141], v[236:237], v[178:179]
	v_pk_fma_f32 v[146:147], v[142:143], v[210:211], v[146:147]
	v_pk_fma_f32 v[148:149], v[144:145], v[212:213], v[148:149]
	v_pk_fma_f32 v[150:151], v[142:143], v[214:215], v[150:151]
	v_pk_fma_f32 v[152:153], v[144:145], v[216:217], v[152:153]
	v_pk_fma_f32 v[154:155], v[142:143], v[218:219], v[154:155]
	v_pk_fma_f32 v[156:157], v[144:145], v[220:221], v[156:157]
	v_pk_fma_f32 v[158:159], v[142:143], v[222:223], v[158:159]
	v_pk_fma_f32 v[160:161], v[144:145], v[224:225], v[160:161]
	v_pk_fma_f32 v[162:163], v[142:143], v[226:227], v[162:163]
	v_pk_fma_f32 v[164:165], v[144:145], v[228:229], v[164:165]
	v_pk_fma_f32 v[166:167], v[142:143], v[230:231], v[166:167]
	v_pk_fma_f32 v[168:169], v[144:145], v[232:233], v[168:169]
	v_pk_fma_f32 v[172:173], v[142:143], v[234:235], v[172:173]
	v_pk_fma_f32 v[174:175], v[144:145], v[236:237], v[174:175]
	v_pk_fma_f32 v[176:177], v[142:143], v[238:239], v[176:177]
	v_pk_fma_f32 v[178:179], v[144:145], v[240:241], v[178:179]
	v_cvt_pk_bf16_f32 v180, v146, v150
	v_cvt_pk_bf16_f32 v181, v154, v158
	v_cvt_pk_bf16_f32 v182, v162, v166
	v_cvt_pk_bf16_f32 v183, v172, v176
	global_store_dwordx4 v185, v[180:183], s[2:3] offset:96
	s_nop 1
	v_cvt_pk_bf16_f32 v180, v147, v151
	v_cvt_pk_bf16_f32 v181, v155, v159
	v_cvt_pk_bf16_f32 v182, v163, v167
	v_cvt_pk_bf16_f32 v183, v173, v177
	global_store_dwordx4 v170, v[180:183], s[2:3] offset:96
	s_nop 1
	v_cvt_pk_bf16_f32 v180, v148, v152
	v_cvt_pk_bf16_f32 v181, v156, v160
	v_cvt_pk_bf16_f32 v182, v164, v168
	v_cvt_pk_bf16_f32 v183, v174, v178
	global_store_dwordx4 v201, v[180:183], s[2:3] offset:96
	s_nop 1
	v_cvt_pk_bf16_f32 v180, v149, v153
	v_cvt_pk_bf16_f32 v181, v157, v161
	v_cvt_pk_bf16_f32 v182, v165, v169
	v_cvt_pk_bf16_f32 v183, v175, v179
	global_store_dwordx4 v184, v[180:183], s[2:3] offset:96
	s_nop 1
	s_waitcnt vmcnt(28)
	s_cmpk_eq_i32 s20, 0x3fc0
	s_cbranch_scc0 .Lhp_nz1
	v_mov_b32_e32 v132, 0
	v_mov_b32_e32 v133, 0
; __device__ __forceinline__ unsigned pk2(float lo, float hi) { unsigned r; asm volatile("v_cvt_pk_bf16_f32 %0, %1, %2" : "=v"(r) : "v"(lo), "v"(hi)); return r; }
; __device__ __forceinline__ float bf2f(bf16_t v) { return __uint_as_float(((unsigned)v) << 16); }
; __device__ __forceinline__ void hyena_prep(const bf16_t* __restrict__ PA, const float* __restrict__ cb  , bf16_t* ZT0, bf16_t* G1T, bf16_t* G2T) {
;     ...
;         bf16_t* dst = (arr == 0 ? ZT0 : (arr == 1 ? G1T : G2T)) + (size_t)c * L_ + t0;
;         bf16_t raw[66];
; #pragma unroll
;         for (int k = 0; k < 66; ++k) { const int tt = t0 - 1 + k; raw[k] = (tt >= 0 && tt < L_) ? src[(size_t)tt * 3072] : (bf16_t)0; }
; #pragma unroll
;         for (int i8 = 0; i8 < 8; ++i8) {
;             float o[8];
; #pragma unroll
;             for (int k = 0; k < 8; ++k) o[k] = w0 * bf2f(raw[i8 * 8 + k]) + w1 * bf2f(raw[i8 * 8 + k + 1]) + w2 * bf2f(raw[i8 * 8 + k + 2]);
;             u32x4 w; w.x = pk2(o[0], o[1]); w.y = pk2(o[2], o[3]); w.z = pk2(o[4], o[5]); w.w = pk2(o[6], o[7]);
;             *(u32x4*)(dst + i8 * 8) = w;
;         }
.Lhp_nz1:
	v_lshlrev_b32_e32 v202, 16, v114
	v_and_b32_e32 v203, 0xffff0000, v114
	v_lshlrev_b32_e32 v204, 16, v115
	v_and_b32_e32 v205, 0xffff0000, v115
	v_lshlrev_b32_e32 v206, 16, v116
	v_and_b32_e32 v207, 0xffff0000, v116
	v_lshlrev_b32_e32 v208, 16, v117
	v_and_b32_e32 v209, 0xffff0000, v117
	v_lshlrev_b32_e32 v210, 16, v118
	v_and_b32_e32 v211, 0xffff0000, v118
	v_lshlrev_b32_e32 v212, 16, v119
	v_and_b32_e32 v213, 0xffff0000, v119
	v_lshlrev_b32_e32 v214, 16, v120
	v_and_b32_e32 v215, 0xffff0000, v120
	v_lshlrev_b32_e32 v216, 16, v121
	v_and_b32_e32 v217, 0xffff0000, v121
	v_lshlrev_b32_e32 v218, 16, v122
	v_and_b32_e32 v219, 0xffff0000, v122
	v_lshlrev_b32_e32 v220, 16, v123
	v_and_b32_e32 v221, 0xffff0000, v123
	v_lshlrev_b32_e32 v222, 16, v124
	v_and_b32_e32 v223, 0xffff0000, v124
	v_lshlrev_b32_e32 v224, 16, v125
	v_and_b32_e32 v225, 0xffff0000, v125
	v_lshlrev_b32_e32 v226, 16, v126
	v_and_b32_e32 v227, 0xffff0000, v126
	v_lshlrev_b32_e32 v228, 16, v127
	v_and_b32_e32 v229, 0xffff0000, v127
	v_lshlrev_b32_e32 v230, 16, v128
	v_and_b32_e32 v231, 0xffff0000, v128
	v_lshlrev_b32_e32 v232, 16, v129
	v_and_b32_e32 v233, 0xffff0000, v129
	v_lshlrev_b32_e32 v234, 16, v130
	v_and_b32_e32 v235, 0xffff0000, v130
	v_lshlrev_b32_e32 v236, 16, v131
	v_and_b32_e32 v237, 0xffff0000, v131
	v_lshlrev_b32_e32 v238, 16, v132
	v_and_b32_e32 v239, 0xffff0000, v132
	v_lshlrev_b32_e32 v240, 16, v133
	v_and_b32_e32 v241, 0xffff0000, v133
	v_pk_mul_f32 v[146:147], v[134:135], v[202:203]
	v_pk_mul_f32 v[148:149], v[136:137], v[204:205]
	v_pk_mul_f32 v[150:151], v[134:135], v[206:207]
	v_pk_mul_f32 v[152:153], v[136:137], v[208:209]
	v_pk_mul_f32 v[154:155], v[134:135], v[210:211]
	v_pk_mul_f32 v[156:157], v[136:137], v[212:213]
	v_pk_mul_f32 v[158:159], v[134:135], v[214:215]
	v_pk_mul_f32 v[160:161], v[136:137], v[216:217]
	v_pk_mul_f32 v[162:163], v[134:135], v[218:219]
	v_pk_mul_f32 v[164:165], v[136:137], v[220:221]
	v_pk_mul_f32 v[166:167], v[134:135], v[222:223]
	v_pk_mul_f32 v[168:169], v[136:137], v[224:225]
	v_pk_mul_f32 v[172:173], v[134:135], v[226:227]
	v_pk_mul_f32 v[174:175], v[136:137], v[228:229]
	v_pk_mul_f32 v[176:177], v[134:135], v[230:231]
	v_pk_mul_f32 v[178:179], v[136:137], v[232:233]
	v_pk_fma_f32 v[146:147], v[138:139], v[206:207], v[146:147]
	v_pk_fma_f32 v[148:149], v[140:141], v[208:209], v[148:149]
	v_pk_fma_f32 v[150:151], v[138:139], v[210:211], v[150:151]
	v_pk_fma_f32 v[152:153], v[140:141], v[212:213], v[152:153]
	v_pk_fma_f32 v[154:155], v[138:139], v[214:215], v[154:155]
	v_pk_fma_f32 v[156:157], v[140:141], v[216:217], v[156:157]
	v_pk_fma_f32 v[158:159], v[138:139], v[218:219], v[158:159]
	v_pk_fma_f32 v[160:161], v[140:141], v[220:221], v[160:161]
	v_pk_fma_f32 v[162:163], v[138:139], v[222:223], v[162:163]
	v_pk_fma_f32 v[164:165], v[140:141], v[224:225], v[164:165]
	v_pk_fma_f32 v[166:167], v[138:139], v[226:227], v[166:167]
	v_pk_fma_f32 v[168:169], v[140:141], v[228:229], v[168:169]
	v_pk_fma_f32 v[172:173], v[138:139], v[230:231], v[172:173]
	v_pk_fma_f32 v[174:175], v[140:141], v[232:233], v[174:175]
	v_pk_fma_f32 v[176:177], v[138:139], v[234:235], v[176:177]
	v_pk_fma_f32 v[178:179], v[140:141], v[236:237], v[178:179]
	v_pk_fma_f32 v[146:147], v[142:143], v[210:211], v[146:147]
	v_pk_fma_f32 v[148:149], v[144:145], v[212:213], v[148:149]
	v_pk_fma_f32 v[150:151], v[142:143], v[214:215], v[150:151]
	v_pk_fma_f32 v[152:153], v[144:145], v[216:217], v[152:153]
	v_pk_fma_f32 v[154:155], v[142:143], v[218:219], v[154:155]
	v_pk_fma_f32 v[156:157], v[144:145], v[220:221], v[156:157]
	v_pk_fma_f32 v[158:159], v[142:143], v[222:223], v[158:159]
	v_pk_fma_f32 v[160:161], v[144:145], v[224:225], v[160:161]
	v_pk_fma_f32 v[162:163], v[142:143], v[226:227], v[162:163]
	v_pk_fma_f32 v[164:165], v[144:145], v[228:229], v[164:165]
	v_pk_fma_f32 v[166:167], v[142:143], v[230:231], v[166:167]
	v_pk_fma_f32 v[168:169], v[144:145], v[232:233], v[168:169]
	v_pk_fma_f32 v[172:173], v[142:143], v[234:235], v[172:173]
	v_pk_fma_f32 v[174:175], v[144:145], v[236:237], v[174:175]
	v_pk_fma_f32 v[176:177], v[142:143], v[238:239], v[176:177]
	v_pk_fma_f32 v[178:179], v[144:145], v[240:241], v[178:179]
	v_cvt_pk_bf16_f32 v180, v146, v150
	v_cvt_pk_bf16_f32 v181, v154, v158
	v_cvt_pk_bf16_f32 v182, v162, v166
	v_cvt_pk_bf16_f32 v183, v172, v176
	global_store_dwordx4 v185, v[180:183], s[2:3] offset:112
	s_nop 1
	v_cvt_pk_bf16_f32 v180, v147, v151
	v_cvt_pk_bf16_f32 v181, v155, v159
	v_cvt_pk_bf16_f32 v182, v163, v167
	v_cvt_pk_bf16_f32 v183, v173, v177
	global_store_dwordx4 v170, v[180:183], s[2:3] offset:112
	s_nop 1
	v_cvt_pk_bf16_f32 v180, v148, v152
	v_cvt_pk_bf16_f32 v181, v156, v160
	v_cvt_pk_bf16_f32 v182, v164, v168
	v_cvt_pk_bf16_f32 v183, v174, v178
	global_store_dwordx4 v201, v[180:183], s[2:3] offset:112
	s_nop 1
	v_cvt_pk_bf16_f32 v180, v149, v153
	v_cvt_pk_bf16_f32 v181, v157, v161
	v_cvt_pk_bf16_f32 v182, v165, v169
	v_cvt_pk_bf16_f32 v183, v175, v179
	global_store_dwordx4 v184, v[180:183], s[2:3] offset:112
.Lhp_done:
	s_or_b64 exec, exec, s[4:5]
	s_branch .LBB0_220
.Lhp_orig:
	v_readlane_b32 s0, v246, 27
	s_waitcnt lgkmcnt(0)
	v_ashrrev_i32_e32 v1, 31, v0
	v_readlane_b32 s1, v246, 28
	v_lshlrev_b64 v[4:5], 15, v[0:1]
	s_nop 0
	v_lshl_add_u64 v[2:3], v[0:1], 1, s[0:1]
	v_readlane_b32 s0, v245, 25
	v_readlane_b32 s1, v245, 26
	s_nop 1
	v_lshl_add_u64 v[4:5], s[0:1], 0, v[4:5]
	v_readlane_b32 s0, v248, 13
	s_mov_b32 s1, s86
	s_branch .LBB0_216
